# final LayerNorm: dropped the unused in-place bf16 row stores (workspace rows are never read after the last layer)
# speedup vs baseline: 1.0111x; 1.0052x over previous
; DI unsigned pack2(float a, float b) { f32x2_t v = {a, b}; return __builtin_bit_cast(unsigned, __builtin_convertvector(v, bf16x2_t)); }
; DI float lo2f(unsigned v) { return __uint_as_float(v << 16); }
; DI float hi2f(unsigned v) { return __uint_as_float(v & 0xffff0000u); }
; DI float wave_sum(float v) { for (int o = 32; o >= 1; o >>= 1) v += __shfl_xor(v, o); return v; }
; DI void ln_phase(int wvs, bf16_t* HB, const float* __restrict__ g, const float* __restrict__ bta, float* fout, bool dostore = true) {
;   const int tid = opaque_tid(wvs);
;   const int lane = tid & 63, w = tid >> 6;
;   for (int row = blockIdx.x * 8 + w; row < MTOT; row += gridDim.x * 8) {
;     bf16_t* p = HB + (size_t)row * 1024;
;     float v[16];
;     float s = 0.f;
; #pragma unroll
;     for (int i = 0; i < 2; ++i) {
;       const u32x4 raw = *(const u32x4*)(p + i * 512 + lane * 8);
; #pragma unroll
;       for (int j = 0; j < 4; ++j) { v[i * 8 + 2 * j] = lo2f(raw[j]); v[i * 8 + 2 * j + 1] = hi2f(raw[j]); }
;     }
; #pragma unroll
;     for (int i = 0; i < 16; ++i) s += v[i];
;     const float mean = wave_sum(s) * (1.f / 1024.f);
;     float q = 0.f;
; #pragma unroll
;     for (int i = 0; i < 16; ++i) { v[i] -= mean; q += v[i] * v[i]; }
;     const float rstd = rsqrtf(wave_sum(q) * (1.f / 1024.f) + 1e-5f);
; #pragma unroll
;     for (int i = 0; i < 2; ++i) {
;       const int c = i * 512 + lane * 8;
;       const float4 g0 = *(const float4*)(g + c), g1 = *(const float4*)(g + c + 4), b0 = *(const float4*)(bta + c), b1 = *(const float4*)(bta + c + 4);
;       float o[8];
;       o[0] = v[i * 8 + 0] * rstd * g0.x + b0.x; o[1] = v[i * 8 + 1] * rstd * g0.y + b0.y; o[2] = v[i * 8 + 2] * rstd * g0.z + b0.z; o[3] = v[i * 8 + 3] * rstd * g0.w + b0.w;
;       o[4] = v[i * 8 + 4] * rstd * g1.x + b1.x; o[5] = v[i * 8 + 5] * rstd * g1.y + b1.y; o[6] = v[i * 8 + 6] * rstd * g1.z + b1.z; o[7] = v[i * 8 + 7] * rstd * g1.w + b1.w;
;       if (dostore) {
;         u32x4 pk; pk[0] = pack2(o[0], o[1]); pk[1] = pack2(o[2], o[3]); pk[2] = pack2(o[4], o[5]); pk[3] = pack2(o[6], o[7]);
;         *(u32x4*)(p + c) = pk;
;         if (fout) {
;           *(float4*)(fout + (size_t)row * 1024 + c) = make_float4(o[0], o[1], o[2], o[3]);
;           *(float4*)(fout + (size_t)row * 1024 + c + 4) = make_float4(o[4], o[5], o[6], o[7]);
;         }
;       }
;     }
;   }
; }
.LBB0_1445:
	v_ashrrev_i32_e32 v41, 31, v40
	v_lshlrev_b64 v[32:33], 11, v[40:41]
	v_lshl_add_u64 v[46:47], v[44:45], 0, v[32:33]
	global_load_dwordx4 v[32:35], v[46:47], off
	global_load_dwordx4 v[36:39], v[46:47], off offset:1024
	v_lshlrev_b64 v[48:49], 12, v[40:41]
	v_readlane_b32 s6, v253, 1
	v_readlane_b32 s7, v253, 2
	v_lshl_add_u64 v[48:49], s[10:11], 0, v[48:49]
	v_lshlrev_b32_e32 v128, 2, v42
	s_waitcnt vmcnt(1)
	v_lshlrev_b32_e32 v52, 16, v32
	v_and_b32_e32 v53, 0xffff0000, v32
	v_add_f32_e32 v32, 0, v52
	v_add_f32_e32 v41, v32, v53
	v_lshlrev_b32_e32 v32, 16, v33
	v_and_b32_e32 v33, 0xffff0000, v33
	v_add_f32_e32 v41, v41, v32
	v_add_f32_e32 v41, v41, v33
	v_lshlrev_b32_e32 v56, 16, v34
	v_and_b32_e32 v57, 0xffff0000, v34
	v_add_f32_e32 v34, v41, v56
	v_add_f32_e32 v41, v34, v57
	v_lshlrev_b32_e32 v34, 16, v35
	v_and_b32_e32 v35, 0xffff0000, v35
	v_add_f32_e32 v41, v41, v34
	s_waitcnt vmcnt(0)
	v_lshlrev_b32_e32 v50, 16, v36
	v_add_f32_e32 v41, v41, v35
	v_and_b32_e32 v51, 0xffff0000, v36
	v_add_f32_e32 v41, v41, v50
	v_lshlrev_b32_e32 v36, 16, v37
	v_add_f32_e32 v41, v41, v51
	v_and_b32_e32 v37, 0xffff0000, v37
	v_add_f32_e32 v41, v41, v36
	v_lshlrev_b32_e32 v54, 16, v38
	v_add_f32_e32 v41, v41, v37
	v_and_b32_e32 v55, 0xffff0000, v38
	v_add_f32_e32 v41, v41, v54
	v_lshlrev_b32_e32 v38, 16, v39
	v_add_f32_e32 v41, v41, v55
	v_and_b32_e32 v39, 0xffff0000, v39
	v_add_f32_e32 v41, v41, v38
	v_add_f32_e32 v41, v41, v39
	ds_bpermute_b32 v58, v43, v41
	s_waitcnt lgkmcnt(0)
	v_add_f32_e32 v41, v41, v58
	ds_bpermute_b32 v58, v60, v41
	s_waitcnt lgkmcnt(0)
	v_add_f32_e32 v41, v41, v58
	ds_bpermute_b32 v58, v61, v41
	s_waitcnt lgkmcnt(0)
	v_add_f32_e32 v41, v41, v58
	ds_bpermute_b32 v58, v62, v41
	s_waitcnt lgkmcnt(0)
	v_add_f32_e32 v41, v41, v58
	ds_bpermute_b32 v58, v63, v41
	s_waitcnt lgkmcnt(0)
	v_add_f32_e32 v41, v41, v58
	ds_bpermute_b32 v58, v64, v41
	s_waitcnt lgkmcnt(0)
	v_add_f32_e32 v41, v41, v58
	v_mul_f32_e32 v58, 0x3a800000, v41
	v_pk_add_f32 v[66:67], v[52:53], v[58:59] op_sel_hi:[1,0] neg_lo:[0,1] neg_hi:[0,1]
	v_pk_add_f32 v[32:33], v[32:33], v[58:59] op_sel_hi:[1,0] neg_lo:[0,1] neg_hi:[0,1]
	v_pk_mul_f32 v[68:69], v[66:67], v[66:67]
	v_pk_mul_f32 v[70:71], v[32:33], v[32:33]
	v_add_f32_e32 v41, v68, v69
	v_pk_add_f32 v[72:73], v[56:57], v[58:59] op_sel_hi:[1,0] neg_lo:[0,1] neg_hi:[0,1]
	v_add_f32_e32 v41, v70, v41
	v_pk_mul_f32 v[74:75], v[72:73], v[72:73]
	v_add_f32_e32 v41, v71, v41
	v_pk_add_f32 v[34:35], v[34:35], v[58:59] op_sel_hi:[1,0] neg_lo:[0,1] neg_hi:[0,1]
	v_add_f32_e32 v41, v74, v41
	v_pk_mul_f32 v[76:77], v[34:35], v[34:35]
	v_add_f32_e32 v41, v75, v41
	v_pk_add_f32 v[50:51], v[50:51], v[58:59] op_sel_hi:[1,0] neg_lo:[0,1] neg_hi:[0,1]
	v_add_f32_e32 v41, v76, v41
	v_pk_mul_f32 v[78:79], v[50:51], v[50:51]
	v_add_f32_e32 v41, v77, v41
	v_pk_add_f32 v[52:53], v[36:37], v[58:59] op_sel_hi:[1,0] neg_lo:[0,1] neg_hi:[0,1]
	v_add_f32_e32 v41, v78, v41
	v_pk_mul_f32 v[36:37], v[52:53], v[52:53]
	v_add_f32_e32 v41, v79, v41
	v_pk_add_f32 v[54:55], v[54:55], v[58:59] op_sel_hi:[1,0] neg_lo:[0,1] neg_hi:[0,1]
	v_add_f32_e32 v36, v36, v41
	v_pk_mul_f32 v[80:81], v[54:55], v[54:55]
	v_add_f32_e32 v36, v37, v36
	v_pk_add_f32 v[56:57], v[38:39], v[58:59] op_sel_hi:[1,0] neg_lo:[0,1] neg_hi:[0,1]
	v_add_f32_e32 v36, v80, v36
	v_pk_mul_f32 v[38:39], v[56:57], v[56:57]
	v_add_f32_e32 v36, v81, v36
	v_add_f32_e32 v36, v38, v36
	v_add_f32_e32 v36, v39, v36
	ds_bpermute_b32 v37, v43, v36
	v_cndmask_b32_e64 v41, 0, 1, s[6:7]
	v_cmp_ne_u32_e64 s[40:41], 1, v41
	s_waitcnt lgkmcnt(0)
	v_add_f32_e32 v36, v36, v37
	ds_bpermute_b32 v37, v60, v36
	s_waitcnt lgkmcnt(0)
	v_add_f32_e32 v36, v36, v37
	ds_bpermute_b32 v37, v61, v36
	s_waitcnt lgkmcnt(0)
	v_add_f32_e32 v36, v36, v37
	ds_bpermute_b32 v37, v62, v36
	s_waitcnt lgkmcnt(0)
	v_add_f32_e32 v36, v36, v37
	ds_bpermute_b32 v37, v63, v36
	s_waitcnt lgkmcnt(0)
	v_add_f32_e32 v36, v36, v37
	ds_bpermute_b32 v37, v64, v36
	s_waitcnt lgkmcnt(0)
	v_add_f32_e32 v36, v36, v37
	v_fmamk_f32 v36, v36, 0x3a800000, v177
	v_cmp_gt_f32_e32 vcc, s75, v36
	v_mul_f32_e32 v37, 0x4b800000, v36
	s_nop 0
	v_cndmask_b32_e32 v36, v36, v37, vcc
	v_rsq_f32_e32 v36, v36
	s_nop 0
	v_mul_f32_e32 v37, 0x45800000, v36
	v_cndmask_b32_e32 v58, v36, v37, vcc
	v_pk_mul_f32 v[32:33], v[32:33], v[58:59] op_sel_hi:[1,0]
	v_pk_mul_f32 v[36:37], v[66:67], v[58:59] op_sel_hi:[1,0]
	v_pk_fma_f32 v[38:39], v[10:11], v[32:33], v[14:15]
	v_pk_mul_f32 v[32:33], v[72:73], v[58:59] op_sel_hi:[1,0]
	v_pk_mul_f32 v[34:35], v[34:35], v[58:59] op_sel_hi:[1,0]
	v_pk_fma_f32 v[36:37], v[8:9], v[36:37], v[12:13]
	v_pk_fma_f32 v[32:33], v[0:1], v[32:33], v[4:5]
	v_pk_fma_f32 v[34:35], v[2:3], v[34:35], v[6:7]
	v_cvt_pk_bf16_f32 v66, v36, v37
	v_cvt_pk_bf16_f32 v67, v38, v39
	v_cvt_pk_bf16_f32 v68, v32, v33
	v_cvt_pk_bf16_f32 v69, v34, v35
	s_andn2_b64 vcc, exec, s[6:7]
	s_cbranch_vccnz .LBB0_1447
	s_nop 0
	v_lshl_add_u64 v[66:67], v[48:49], 0, v[128:129]
	global_store_dwordx4 v[66:67], v[36:39], off
	global_store_dwordx4 v[66:67], v[32:35], off offset:16
.LBB0_1447:
	v_mov_b32_e32 v59, v58
	s_nop 0
	v_pk_mul_f32 v[32:33], v[50:51], v[58:59]
	v_pk_mul_f32 v[34:35], v[56:57], v[58:59]
	v_pk_fma_f32 v[36:37], v[24:25], v[32:33], v[28:29]
	v_pk_mul_f32 v[32:33], v[52:53], v[58:59]
	v_pk_fma_f32 v[34:35], v[18:19], v[34:35], v[22:23]
	v_pk_fma_f32 v[38:39], v[26:27], v[32:33], v[30:31]
	v_pk_mul_f32 v[32:33], v[54:55], v[58:59]
	v_cvt_pk_bf16_f32 v50, v36, v37
	v_pk_fma_f32 v[32:33], v[16:17], v[32:33], v[20:21]
	v_cvt_pk_bf16_f32 v51, v38, v39
	v_cvt_pk_bf16_f32 v52, v32, v33
	v_cvt_pk_bf16_f32 v53, v34, v35
	s_and_b64 vcc, exec, s[40:41]
	s_cbranch_vccnz .LBB0_1444
	v_lshl_add_u64 v[46:47], v[48:49], 0, v[128:129]
	global_store_dwordx4 v[46:47], v[36:39], off offset:2048
	global_store_dwordx4 v[46:47], v[32:35], off offset:2064
	s_branch .LBB0_1444
